# K-start rotation (16 starts) in phase 10 GEMM loop (on v13; phase 12 rotation dropped)
# speedup vs baseline: 1.0129x; 1.0129x over previous
;     __device__ __forceinline__ bool next(int i, Unit& u) const { if (i != 0 || c >= n) return false; u.pm = 0; u.pn = c; u.kt0 = 0; u.nkt = ntk; u.piece = -1; return true; }
; #define PG8_WAIT_V(n) asm volatile("s_waitcnt vmcnt(" #n ")" ::: "memory")
; #define PG8_BAR __builtin_amdgcn_s_barrier()
; template <class Epi, class Sched>
; __device__ __forceinline__ void gemm_phase(LAS unsigned char* lds, const Gemm g, const Sched& S, const Epi& E) {
;     const int tid = threadIdx.x, wid = __builtin_amdgcn_readfirstlane(tid >> 6), lane = tid & 63, wr = wid >> 2, wc = wid & 3, fr = lane & 15, fq = lane >> 4;
;     unsigned voffA[2], voffB[2];
; #pragma unroll
;     for (int i = 0; i < 2; ++i) { int R, C; stage_rc(tid * 16 + i * 8192, R, C); const int Rb = Epi::PERM ? ((R & ~31) + perm32(R & 31)) : R;
;         voffA[i] = (unsigned)(R * g.lda + C) * 2u; voffB[i] = (unsigned)(Rb * g.ldb + C) * 2u; }
;     const size_t kstep = (size_t)(BK * 2);
;     const size_t hstepA = g.a_half ? g.a_half : (size_t)HALF * g.lda * 2, hstepB = g.b_half ? g.b_half : (size_t)HALF * g.ldb * 2;
;     const size_t tstepA = g.a_tile ? g.a_tile : (size_t)BM * g.lda * 2, tstepB = g.b_tile ? g.b_tile : (size_t)BM * g.ldb * 2;
;     const unsigned ldsw = (unsigned)wid * 1024u;
;     const int aoff = lds_byte(wr * 64 + fr, fq * 8), boff = lds_byte(wc * 32 + fr, fq * 8);
;     ...
;     Unit cur, nxt; int ui = 0;
;     if (!S.next(0, cur)) return;
;     f32x4 acc[2][2][4][2];
; #pragma unroll
;     for (int a = 0; a < 2; ++a)
; #pragma unroll
;         for (int b = 0; b < 2; ++b)
; #pragma unroll
;             for (int m = 0; m < 4; ++m)
; #pragma unroll
;                 for (int n = 0; n < 2; ++n) acc[a][b][m][n] = (f32x4){0.f, 0.f, 0.f, 0.f};
;     bf16x8 At[4][2], B0[2][2], B1[2][2];
;     const char* cA = (const char*)g.A + (size_t)cur.pm * tstepA + (size_t)cur.pn * g.a_pn_off + (size_t)cur.kt0 * kstep; const char* cB = (const char*)g.Bt + (size_t)cur.pn * tstepB + (size_t)cur.kt0 * kstep;
;     PG8_STAGE(PG8_SB(0, 0), cB, voffB); PG8_STAGE(PG8_SA(0, 0), cA, voffA); PG8_STAGE(PG8_SB(0, 1), cB + hstepB, voffB); PG8_STAGE(PG8_SA(0, 1), cA + hstepA, voffA);
;     if (wr == 1) PG8_BAR;
;     PG8_WAIT_V(4); PG8_BAR;
;     PG8_STAGE(PG8_SB(1, 0), cB + kstep, voffB); PG8_STAGE(PG8_SA(1, 0), cA + kstep, voffA); PG8_STAGE(PG8_SB(1, 1), cB + hstepB + kstep, voffB);
;     PG8_WAIT_V(6); PG8_BAR;
.LBB0_1646:
	s_cmp_lt_i32 s86, 11
	s_cselect_b64 s[4:5], -1, 0
	s_and_b64 s[6:7], s[4:5], s[6:7]
	s_andn2_b64 vcc, exec, s[6:7]
	s_cbranch_vccnz .LBB0_1693
	s_cmpk_gt_i32 s2, 0x17f
	v_readfirstlane_b32 s3, v160
	s_cbranch_scc1 .LBB0_1693
	s_max_i32 s8, s2, 0x100
	s_and_b32 s16, s8, 7
	s_lshl_b32 s9, s16, 9
	s_cmpk_lt_i32 s2, 0x100
	s_cselect_b64 s[6:7], -1, 0
	s_and_b64 s[6:7], s[6:7], exec
	s_cselect_b32 s6, s2, 0
	s_cselect_b32 s10, 0, s9
	s_ashr_i32 s7, s6, 31
	s_lshr_b32 s7, s7, 29
	s_add_i32 s7, s6, s7
	s_ashr_i32 s7, s7, 3
	s_mulk_i32 s7, 0xff01
	s_lshl_b32 s6, s6, 5
	s_add_i32 s6, s7, s6
	s_ashr_i32 s7, s6, 31
	s_lshr_b32 s7, s7, 26
	s_add_i32 s9, s6, s7
	s_and_b32 s7, s9, 0xffffffc0
	s_sub_i32 s11, s6, s7
	s_bfe_i32 s6, s11, 0x80000
	s_bfe_u32 s6, s6, 0x3000c
	s_add_i32 s13, s11, s6
	s_bfe_i32 s6, s13, 0x80000
	s_sext_i32_i16 s6, s6
	s_ashr_i32 s12, s6, 3
	s_bfe_u32 s14, s8, 0x30003
	s_cmpk_lt_i32 s2, 0x100
	s_cselect_b64 s[6:7], -1, 0
	s_and_b64 s[6:7], s[6:7], exec
	s_cselect_b32 s12, s12, s14
	s_and_b32 s7, s13, 0xf8
	s_ashr_i32 s6, s9, 6
	s_sub_i32 s7, s11, s7
	s_lshl_b32 s6, s6, 3
	s_sext_i32_i8 s7, s7
	s_addk_i32 s8, 0xff00
	s_add_i32 s11, s6, s7
	s_lshr_b32 s6, s8, 6
	s_add_i32 s13, s6, 32
	s_cmpk_lt_i32 s2, 0x100
	s_cselect_b64 s[6:7], -1, 0
	s_and_b64 s[8:9], s[6:7], exec
	s_cselect_b32 s14, s11, s13
	s_add_u32 s38, s84, 0xa139000
	s_addc_u32 s39, s85, 0
	s_waitcnt vmcnt(0)
	v_lshlrev_b32_e32 v0, 4, v160
	s_add_u32 s40, s84, 0x6700000
	v_and_b32_e32 v1, 32, v160
	v_bfe_u32 v10, v160, 2, 4
	v_lshrrev_b32_e32 v2, 3, v160
	s_movk_i32 s8, 0x70
	v_add_u32_e32 v11, 0x2000, v0
	s_addc_u32 s41, s85, 0
	v_bitop3_b32 v8, v0, v1, 48 bitop3:0x6c
	v_and_or_b32 v2, v2, s8, v10
	v_lshrrev_b32_e32 v0, 7, v11
	s_movk_i32 s8, 0xf0
	s_ashr_i32 s15, s14, 31
	v_and_or_b32 v0, v0, s8, v10
	s_lshl_b64 s[8:9], s[14:15], 20
	s_add_u32 s11, s38, s8
	s_addc_u32 s15, s39, s9
	s_ashr_i32 s13, s12, 31
	s_lshl_b64 s[8:9], s[12:13], 20
	s_add_u32 s8, s40, s8
	s_addc_u32 s9, s41, s9
	s_add_u32 s18, s8, s10
	s_addc_u32 s19, s9, 0
	s_add_u32 s20, s11, s10
	s_addc_u32 s21, s15, 0
	s_bfe_u32 s79, s2, 0x40003
	s_lshl_b32 s79, s79, 8
	s_cmpk_lt_u32 s2, 0x100
	s_cselect_b32 s79, s79, 0
	s_add_u32 s18, s18, s79
	s_addc_u32 s19, s19, 0
	s_add_u32 s20, s20, s79
	s_addc_u32 s21, s21, 0
	s_lshr_b32 s13, s3, 6
	s_lshr_b32 s15, s3, 8
	s_lshl_b32 s42, s13, 10
	s_add_u32 s8, s20, 0x80000
	s_addc_u32 s9, s21, 0
	v_and_b32_e32 v9, 64, v160
	s_add_u32 s10, s18, 0x80000
	v_or_b32_e32 v1, v8, v9
	s_addc_u32 s11, s19, 0
	s_add_i32 s43, s42, 0
	v_lshl_or_b32 v128, v2, 12, v1
	s_add_i32 m0, s43, 0x10000
	v_lshl_or_b32 v130, v0, 12, v1
	global_load_lds_dwordx4 v128, s[18:19]
	s_add_i32 m0, s43, 0x12000
	s_add_i32 s44, s43, 0x2000
	global_load_lds_dwordx4 v130, s[18:19]
	s_mov_b32 m0, s43
	s_add_i32 s45, s43, 0x4000
	global_load_lds_dwordx4 v128, s[20:21]
	s_mov_b32 m0, s44
	s_add_i32 s46, s43, 0x6000
	global_load_lds_dwordx4 v130, s[20:21]
	s_add_i32 m0, s43, 0x14000
	v_mov_b32_e32 v133, 0
	global_load_lds_dwordx4 v128, s[10:11]
	s_add_i32 m0, s43, 0x16000
	v_mov_b32_e32 v129, v133
	global_load_lds_dwordx4 v130, s[10:11]
	s_mov_b32 m0, s45
	v_mov_b32_e32 v131, v133
	global_load_lds_dwordx4 v128, s[8:9]
	s_mov_b32 m0, s46
	s_mov_b32 s17, 0
	global_load_lds_dwordx4 v130, s[8:9]
	s_load_dwordx4 s[8:11], s[0:1], 0x0
	s_movk_i32 s47, 0x2000
	v_lshl_add_u64 v[0:1], s[18:19], 0, v[128:129]
	v_lshl_add_u64 v[2:3], s[18:19], 0, v[130:131]
	v_lshl_add_u64 v[4:5], s[20:21], 0, v[128:129]
	s_cmp_lg_u32 s15, 1
	v_lshl_add_u64 v[6:7], s[20:21], 0, v[130:131]
	s_cbranch_scc1 .LBB0_1650
	s_barrier
.LBB0_1650:
	s_add_u32 s22, s84, 0x7884000
	s_addc_u32 s23, s85, 0
	s_add_u32 s48, s84, 0x11d39000
	s_addc_u32 s49, s85, 0
	s_and_b64 s[6:7], s[6:7], exec
	s_cselect_b32 s67, 32, 4
	s_cselect_b32 s16, -1, s16
	s_mov_b64 s[24:25], 0x80
	s_add_u32 s6, s18, 0x80080
	v_lshl_add_u64 v[0:1], v[0:1], 0, s[24:25]
	s_addc_u32 s7, s19, 0
	s_add_i32 m0, s43, 0x18000
	v_lshl_add_u64 v[2:3], v[2:3], 0, s[24:25]
	s_waitcnt vmcnt(4)
	s_barrier
	global_load_lds_dwordx4 v[0:1], off
	s_add_i32 m0, s43, 0x1a000
	s_add_i32 s50, s43, 0x8000
	v_lshl_add_u64 v[4:5], v[4:5], 0, s[24:25]
	global_load_lds_dwordx4 v[2:3], off
	s_mov_b32 m0, s50
	s_add_i32 s51, s43, 0xa000
	v_lshl_add_u64 v[6:7], v[6:7], 0, s[24:25]
	global_load_lds_dwordx4 v[4:5], off
	s_mov_b32 m0, s51
	v_lshl_add_u64 v[12:13], s[6:7], 0, v[128:129]
	global_load_lds_dwordx4 v[6:7], off
	s_add_i32 m0, s43, 0x1c000
	v_lshl_add_u64 v[14:15], s[6:7], 0, v[130:131]
	global_load_lds_dwordx4 v[12:13], off
	s_add_i32 m0, s43, 0x1e000
	v_bfe_u32 v0, v160, 4, 2
	global_load_lds_dwordx4 v[14:15], off
	v_and_b32_e32 v152, 15, v160
	v_lshlrev_b32_e32 v1, 4, v0
	v_lshlrev_b32_e32 v2, 6, v160
	s_movk_i32 s6, 0x3c0
	v_and_or_b32 v2, v2, s6, v1
	v_and_b32_e32 v3, 32, v184
	v_lshl_or_b32 v1, v152, 6, v1
	s_lshl_b32 s6, s15, 13
	v_bitop3_b32 v1, v1, s6, v3 bitop3:0xde
	s_lshl_b32 s6, s13, 5
	s_and_b32 s6, s6, 0x60
	s_lshl_b32 s7, s6, 7
	v_lshl_or_b32 v154, v0, 2, s6
	v_lshlrev_b32_e32 v0, 9, v160
	v_bitop3_b32 v153, s7, v2, v3 bitop3:0xf6
	v_and_b32_e32 v0, 0x70000, v0
	v_lshlrev_b32_e32 v2, 12, v10
	s_load_dwordx2 s[26:27], s[0:1], 0xc0
	v_or3_b32 v0, v8, v0, v2
	v_add_u32_e32 v134, v0, v9
	v_lshlrev_b32_e32 v0, 5, v11
	s_waitcnt vmcnt(6)
	v_and_b32_e32 v0, 0xf0000, v0
	v_or3_b32 v0, v8, v0, v2
	s_add_i32 s53, 0, 0x10000
	s_add_i32 s55, 0, 0x14000
	s_lshl_b32 s52, s15, 6
	v_mov_b32_e32 v135, v133
	v_add_u32_e32 v136, v0, v9
	v_mov_b32_e32 v137, v133
	v_add_u32_e32 v155, s53, v153
	v_add_u32_e32 v156, 0, v1
	s_mov_b32 s54, 0xc000
	v_add_u32_e32 v157, s55, v153
	s_movk_i32 s56, 0x1fff
	s_movk_i32 s57, 0x1f80
	s_movk_i32 s58, 0x1f7f
	s_movk_i32 s59, 0x1f70
	s_movk_i32 s60, 0x1f6f
	s_movk_i32 s61, 0x1f60
	s_movk_i32 s62, 0x1f5f
	s_movk_i32 s63, 0x1f50
	s_movk_i32 s64, 0x1f4f
	s_mov_b32 s65, s17
	s_sub_u32 s18, s18, s79
	s_subb_u32 s19, s19, 0
	s_sub_u32 s20, s20, s79
	s_subb_u32 s21, s21, 0
	s_barrier
	s_branch .LBB0_1652

;     __device__ __forceinline__ bool next(int i, Unit& u) const { if (i != 0 || c >= n) return false; u.pm = 0; u.pn = c; u.kt0 = 0; u.nkt = ntk; u.piece = -1; return true; }
; template <class Epi, class Sched>
; __device__ __forceinline__ void gemm_phase(LAS unsigned char* lds, const Gemm g, const Sched& S, const Epi& E) {
;     ...
;     for (;;) {
;         const bool has_next = S.next(ui + 1, nxt);
;         const char* nA = has_next ? (const char*)g.A + (size_t)nxt.pm * tstepA + (size_t)nxt.pn * g.a_pn_off + (size_t)nxt.kt0 * kstep : cA; const char* nB = has_next ? (const char*)g.Bt + (size_t)nxt.pn * tstepB + (size_t)nxt.kt0 * kstep : cB;
;         const int nt = cur.nkt;
.LBB0_1652:
	s_mov_b32 s80, s79
	s_add_i32 s65, s65, 1
	s_mov_b32 s68, s12
	s_mul_i32 s12, s65, s96
	s_add_i32 s35, s12, s2
	s_bfe_u32 s79, s35, 0x40003
	s_lshl_b32 s79, s79, 8
	s_cmpk_lt_u32 s35, 0x100
	s_cselect_b32 s79, s79, 0
	s_mov_b32 s69, s14
	s_max_i32 s14, s35, 0x100
	s_and_b32 s66, s14, 7
	s_lshl_b32 s15, s66, 9
	s_cmpk_lt_i32 s35, 0x100
	s_cselect_b64 s[12:13], -1, 0
	s_and_b64 s[12:13], s[12:13], exec
	s_cselect_b32 s12, s35, 0
	s_cselect_b32 s70, 0, s15
	s_ashr_i32 s13, s12, 31
	s_lshr_b32 s13, s13, 29
	s_add_i32 s13, s12, s13
	s_ashr_i32 s15, s13, 3
	s_and_b32 s13, s13, 0x7fffff8
	s_sub_i32 s12, s12, s13
	s_lshl_b32 s12, s12, 5
	s_add_i32 s12, s12, s15
	s_ashr_i32 s13, s12, 31
	s_lshr_b32 s13, s13, 26
	s_add_i32 s15, s12, s13
	s_and_b32 s13, s15, 0xffffffc0
	s_mov_b64 s[36:37], s[18:19]
	s_sub_i32 s18, s12, s13
	s_bfe_i32 s12, s18, 0x80000
	s_bfe_u32 s12, s12, 0x3000c
	s_add_i32 s19, s18, s12
	s_bfe_i32 s12, s19, 0x80000
	s_sext_i32_i16 s12, s12
	s_mov_b64 s[6:7], s[20:21]
	s_ashr_i32 s20, s12, 3
	s_bfe_u32 s21, s14, 0x30003
	s_cmpk_lt_i32 s35, 0x100
	s_cselect_b64 s[12:13], -1, 0
	s_and_b64 s[12:13], s[12:13], exec
	s_cselect_b32 s12, s20, s21
	s_ashr_i32 s13, s15, 6
	s_and_b32 s15, s19, 0xf8
	s_sub_i32 s15, s18, s15
	s_addk_i32 s14, 0xff00
	s_lshl_b32 s13, s13, 3
	s_sext_i32_i8 s15, s15
	s_lshr_b32 s14, s14, 6
	s_add_i32 s13, s13, s15
	s_add_i32 s18, s14, 32
	s_cmpk_lt_i32 s35, 0x100
	s_cselect_b64 s[28:29], -1, 0
	s_and_b64 s[14:15], s[28:29], exec
	s_cselect_b32 s14, s13, s18
	s_cmpk_gt_i32 s35, 0x17f
	s_cselect_b64 s[30:31], -1, 0
	s_ashr_i32 s15, s14, 31
	s_lshl_b64 s[18:19], s[14:15], 20
	s_add_u32 s13, s38, s18
	s_addc_u32 s15, s39, s19
	s_add_u32 s20, s13, s70
	s_addc_u32 s21, s15, 0
	s_ashr_i32 s13, s12, 31
	s_lshl_b64 s[18:19], s[12:13], 20
	s_add_u32 s13, s40, s18
	s_addc_u32 s15, s41, s19
	s_add_u32 s18, s13, s70
	s_addc_u32 s19, s15, 0
	s_cmpk_lt_i32 s35, 0x180
	s_cselect_b32 s13, s21, s7
	s_cselect_b32 s15, s20, s6
	s_cselect_b32 s70, s19, s37
	s_cselect_b32 s71, s18, s36
	s_add_i32 s72, s67, -2
	s_add_u32 s6, s6, 0x80080
	s_addc_u32 s7, s7, 0
	s_add_u32 s73, s36, 0x100
	v_mov_b32_e32 v0, 0
	s_mov_b32 s34, 0
	s_addc_u32 s74, s37, 0
	v_mov_b32_e32 v1, v0
	v_mov_b32_e32 v2, v0
	v_mov_b32_e32 v3, v0
	v_mov_b32_e32 v4, v0
	v_mov_b32_e32 v5, v0
	v_mov_b32_e32 v6, v0
	v_mov_b32_e32 v7, v0
	v_mov_b32_e32 v8, v0
	v_mov_b32_e32 v9, v0
	v_mov_b32_e32 v10, v0
	v_mov_b32_e32 v11, v0
	v_mov_b32_e32 v12, v0
	v_mov_b32_e32 v13, v0
	v_mov_b32_e32 v14, v0
	v_mov_b32_e32 v15, v0
	v_mov_b32_e32 v20, v0
	v_mov_b32_e32 v21, v0
	v_mov_b32_e32 v22, v0
	v_mov_b32_e32 v23, v0
	v_mov_b32_e32 v28, v0
	v_mov_b32_e32 v29, v0
	v_mov_b32_e32 v30, v0
	v_mov_b32_e32 v31, v0
	v_mov_b32_e32 v36, v0
	v_mov_b32_e32 v37, v0
	v_mov_b32_e32 v38, v0
	v_mov_b32_e32 v39, v0
	v_mov_b32_e32 v44, v0
	v_mov_b32_e32 v45, v0
	v_mov_b32_e32 v46, v0
	v_mov_b32_e32 v47, v0
	v_mov_b32_e32 v16, v0
	v_mov_b32_e32 v17, v0
	v_mov_b32_e32 v18, v0
	v_mov_b32_e32 v19, v0
	v_mov_b32_e32 v24, v0
	v_mov_b32_e32 v25, v0
	v_mov_b32_e32 v26, v0
	v_mov_b32_e32 v27, v0
	v_mov_b32_e32 v32, v0
	v_mov_b32_e32 v33, v0
	v_mov_b32_e32 v34, v0
	v_mov_b32_e32 v35, v0
	v_mov_b32_e32 v40, v0
	v_mov_b32_e32 v41, v0
	v_mov_b32_e32 v42, v0
	v_mov_b32_e32 v43, v0
	v_mov_b32_e32 v48, v0
	v_mov_b32_e32 v49, v0
	v_mov_b32_e32 v50, v0
	v_mov_b32_e32 v51, v0
	v_mov_b32_e32 v52, v0
	v_mov_b32_e32 v53, v0
	v_mov_b32_e32 v54, v0
	v_mov_b32_e32 v55, v0
	v_mov_b32_e32 v56, v0
	v_mov_b32_e32 v57, v0
	v_mov_b32_e32 v58, v0
	v_mov_b32_e32 v59, v0
	v_mov_b32_e32 v60, v0
	v_mov_b32_e32 v61, v0
	v_mov_b32_e32 v62, v0
	v_mov_b32_e32 v63, v0
	v_mov_b32_e32 v64, v0
	v_mov_b32_e32 v65, v0
	v_mov_b32_e32 v66, v0
	v_mov_b32_e32 v67, v0
	v_mov_b32_e32 v68, v0
	v_mov_b32_e32 v69, v0
	v_mov_b32_e32 v70, v0
	v_mov_b32_e32 v71, v0
	v_mov_b32_e32 v72, v0
	v_mov_b32_e32 v73, v0
	v_mov_b32_e32 v74, v0
	v_mov_b32_e32 v75, v0
	v_mov_b32_e32 v76, v0
	v_mov_b32_e32 v77, v0
	v_mov_b32_e32 v78, v0
	v_mov_b32_e32 v79, v0
	v_mov_b32_e32 v84, v0
	v_mov_b32_e32 v85, v0
	v_mov_b32_e32 v86, v0
	v_mov_b32_e32 v87, v0
	v_mov_b32_e32 v92, v0
	v_mov_b32_e32 v93, v0
	v_mov_b32_e32 v94, v0
	v_mov_b32_e32 v95, v0
	v_mov_b32_e32 v100, v0
	v_mov_b32_e32 v101, v0
	v_mov_b32_e32 v102, v0
	v_mov_b32_e32 v103, v0
	v_mov_b32_e32 v108, v0
	v_mov_b32_e32 v109, v0
	v_mov_b32_e32 v110, v0
	v_mov_b32_e32 v111, v0
	v_mov_b32_e32 v80, v0
	v_mov_b32_e32 v81, v0
	v_mov_b32_e32 v82, v0
	v_mov_b32_e32 v83, v0
	v_mov_b32_e32 v88, v0
	v_mov_b32_e32 v89, v0
	v_mov_b32_e32 v90, v0
	v_mov_b32_e32 v91, v0
	v_mov_b32_e32 v96, v0
	v_mov_b32_e32 v97, v0
	v_mov_b32_e32 v98, v0
	v_mov_b32_e32 v99, v0
	v_mov_b32_e32 v104, v0
	v_mov_b32_e32 v105, v0
	v_mov_b32_e32 v106, v0
	v_mov_b32_e32 v107, v0
	v_mov_b32_e32 v112, v0
	v_mov_b32_e32 v113, v0
	v_mov_b32_e32 v114, v0
	v_mov_b32_e32 v115, v0
	v_mov_b32_e32 v116, v0
	v_mov_b32_e32 v117, v0
	v_mov_b32_e32 v118, v0
	v_mov_b32_e32 v119, v0
	v_mov_b32_e32 v120, v0
	v_mov_b32_e32 v121, v0
	v_mov_b32_e32 v122, v0
	v_mov_b32_e32 v123, v0
	v_mov_b32_e32 v124, v0
	v_mov_b32_e32 v125, v0
	v_mov_b32_e32 v126, v0
	v_mov_b32_e32 v127, v0
; #define PG8_STAGE(bufoff, gbase, voff) do { _Pragma("unroll") for (int _i = 0; _i < 2; ++_i) \
;         __builtin_amdgcn_global_load_lds((const unsigned*)((const char*)(gbase) + (voff)[_i]), (LAS unsigned*)(lds + (bufoff) + ldsw + _i * 8192), 16, 0, 0); } while (0)
; #define PG8_LDA(dst, b, h) do { _Pragma("unroll") for (int m = 0; m < 4; ++m) _Pragma("unroll") for (int k = 0; k < 2; ++k) dst[m][k] = *(const LAS bf16x8*)(lds + PG8_SA(b, h) + aoff + m * 2048 + k * 1024); } while (0)
; #define PG8_LDB(dst, b, h) do { _Pragma("unroll") for (int n = 0; n < 2; ++n) _Pragma("unroll") for (int k = 0; k < 2; ++k) dst[n][k] = *(const LAS bf16x8*)(lds + PG8_SB(b, h) + boff + n * 2048 + k * 1024); } while (0)
; #define PG8_MMA(ai, bj, At, Bt) do { __builtin_amdgcn_s_setprio(1); _Pragma("unroll") for (int m = 0; m < 4; ++m) _Pragma("unroll") for (int n = 0; n < 2; ++n) _Pragma("unroll") for (int k = 0; k < 2; ++k) \
;         acc[ai][bj][m][n] = __builtin_amdgcn_mfma_f32_16x16x32_bf16(Bt[n][k], At[m][k], acc[ai][bj][m][n], 0, 0, 0); __builtin_amdgcn_s_setprio(0); } while (0)
; #define PG8_WAIT_V(n) asm volatile("s_waitcnt vmcnt(" #n ")" ::: "memory")
; #define PG8_BAR __builtin_amdgcn_s_barrier()
; template <class Epi, class Sched>
; __device__ __forceinline__ void gemm_phase(LAS unsigned char* lds, const Gemm g, const Sched& S, const Epi& E) {
;     ...
;         for (int t = 0; t < nt; t += 2) {
;             const bool last = (t == nt - 2);
;             const char* a1 = cA + (size_t)(t + 1) * kstep;
;             const char* a2 = last ? nA : cA + (size_t)(t + 2) * kstep; const char* b2 = last ? nB : cB + (size_t)(t + 2) * kstep;
;             const char* a3 = a2 + kstep; const char* b3 = b2 + kstep;
;             PG8_LDB(B0, 0, 0); PG8_SCHED; PG8_LDA(At, 0, 0); PG8_STAGE(PG8_SA(1, 1), a1 + hstepA, voffA);
;             PG8_WAIT_L(8); PG8_BAR; PG8_WAIT_L(0); PG8_MMA(0, 0, At, B0); PG8_BAR; PG8_SCHED;
;             PG8_LDB(B1, 0, 1); PG8_STAGE(PG8_SB(0, 0), b2, voffB);
;             PG8_BAR; PG8_WAIT_L(0); if constexpr (!Epi::DIAG) PG8_MMA(0, 1, At, B1); PG8_BAR;
;             PG8_LDA(At, 0, 1); PG8_STAGE(PG8_SA(0, 0), a2, voffA);
;             PG8_BAR; PG8_WAIT_L(0); if constexpr (!Epi::DIAG) PG8_MMA(1, 0, At, B0); PG8_BAR; PG8_SCHED;
;             PG8_STAGE(PG8_SB(0, 1), b2 + hstepB, voffB);
;             PG8_WAIT_V(6); PG8_BAR; PG8_MMA(1, 1, At, B1); PG8_BAR;
.LBB0_1653:
	ds_read_b128 v[138:141], v155
	ds_read_b128 v[142:145], v155 offset:1024
	ds_read_b128 v[146:149], v155 offset:2048
	ds_read_b128 v[162:165], v155 offset:3072
	s_add_i32 s75, s34, 2
	s_add_u32 s81, s80, 0x100
	s_and_b32 s81, s81, 0xfff
	s_add_u32 s35, s6, s81
	s_addc_u32 s36, s7, 0
	s_sub_u32 s35, s35, 0x80080
	s_subb_u32 s36, s36, 0
	s_add_u32 s88, s15, s79
	s_addc_u32 s89, s13, 0
	s_cmp_eq_u32 s72, s34
	s_cselect_b32 s37, s89, s36
	s_cselect_b32 s36, s88, s35
	s_add_u32 s88, s73, s81
	s_addc_u32 s89, s74, 0
	s_sub_u32 s88, s88, 0x100
	s_subb_u32 s89, s89, 0
	s_add_u32 s90, s71, s79
	s_addc_u32 s91, s70, 0
	s_cmp_eq_u32 s72, s34
	s_cselect_b32 s35, s91, s89
	s_cselect_b32 s34, s90, s88
	s_add_u32 s88, s6, s80
	s_addc_u32 s89, s7, 0
	v_lshl_add_u64 v[150:151], s[88:89], 0, v[134:135]
	s_add_i32 m0, s43, 0xc000
	ds_read_b128 v[166:169], v156
	ds_read_b128 v[170:173], v156 offset:1024
	ds_read_b128 v[174:177], v156 offset:2048
	ds_read_b128 v[178:181], v156 offset:3072
	ds_read_b128 v[186:189], v156 offset:4096
	ds_read_b128 v[190:193], v156 offset:5120
	ds_read_b128 v[194:197], v156 offset:6144
	ds_read_b128 v[198:201], v156 offset:7168
	global_load_lds_dwordx4 v[150:151], off
	v_lshl_add_u64 v[150:151], s[88:89], 0, v[136:137]
	s_add_i32 m0, s43, 0xe000
	s_nop 0
	global_load_lds_dwordx4 v[150:151], off
	s_waitcnt lgkmcnt(8)
	s_barrier
	s_waitcnt lgkmcnt(0)
	s_setprio 1
	s_waitcnt lgkmcnt(0)
	v_mfma_f32_16x16x32_bf16 v[124:127], v[138:141], v[166:169], v[124:127]
	v_mfma_f32_16x16x32_bf16 v[120:123], v[146:149], v[166:169], v[120:123]
	v_mfma_f32_16x16x32_bf16 v[116:119], v[138:141], v[174:177], v[116:119]
	v_mfma_f32_16x16x32_bf16 v[112:115], v[146:149], v[174:177], v[112:115]
	v_mfma_f32_16x16x32_bf16 v[104:107], v[138:141], v[186:189], v[104:107]
	v_mfma_f32_16x16x32_bf16 v[96:99], v[146:149], v[186:189], v[96:99]
	v_mfma_f32_16x16x32_bf16 v[88:91], v[138:141], v[194:197], v[88:91]
	v_mfma_f32_16x16x32_bf16 v[80:83], v[146:149], v[194:197], v[80:83]
	v_mfma_f32_16x16x32_bf16 v[124:127], v[142:145], v[170:173], v[124:127]
	v_mfma_f32_16x16x32_bf16 v[120:123], v[162:165], v[170:173], v[120:123]
	v_mfma_f32_16x16x32_bf16 v[116:119], v[142:145], v[178:181], v[116:119]
	v_mfma_f32_16x16x32_bf16 v[112:115], v[162:165], v[178:181], v[112:115]
	v_mfma_f32_16x16x32_bf16 v[104:107], v[142:145], v[190:193], v[104:107]
	v_mfma_f32_16x16x32_bf16 v[96:99], v[162:165], v[190:193], v[96:99]
	v_mfma_f32_16x16x32_bf16 v[88:91], v[142:145], v[198:201], v[88:91]
	v_mfma_f32_16x16x32_bf16 v[80:83], v[162:165], v[198:201], v[80:83]
	s_setprio 0
	s_barrier
	s_add_i32 s76, s53, s42
	v_lshl_add_u64 v[150:151], s[34:35], 0, v[128:129]
	s_mov_b32 m0, s76
	ds_read_b128 v[202:205], v157
	ds_read_b128 v[206:209], v157 offset:1024
	ds_read_b128 v[210:213], v157 offset:2048
	ds_read_b128 v[214:217], v157 offset:3072
	global_load_lds_dwordx4 v[150:151], off
	v_lshl_add_u64 v[158:159], s[34:35], 0, v[130:131]
	s_add_i32 m0, s76, 0x2000
	s_nop 0
	global_load_lds_dwordx4 v[158:159], off
	s_barrier
	s_waitcnt lgkmcnt(0)
	s_setprio 1
	s_waitcnt lgkmcnt(0)
	v_mfma_f32_16x16x32_bf16 v[108:111], v[202:205], v[166:169], v[108:111]
	v_mfma_f32_16x16x32_bf16 v[100:103], v[210:213], v[166:169], v[100:103]
	v_mfma_f32_16x16x32_bf16 v[92:95], v[202:205], v[174:177], v[92:95]
	v_mfma_f32_16x16x32_bf16 v[84:87], v[210:213], v[174:177], v[84:87]
	v_mfma_f32_16x16x32_bf16 v[76:79], v[202:205], v[186:189], v[76:79]
	v_mfma_f32_16x16x32_bf16 v[72:75], v[210:213], v[186:189], v[72:75]
	v_mfma_f32_16x16x32_bf16 v[68:71], v[202:205], v[194:197], v[68:71]
	v_mfma_f32_16x16x32_bf16 v[64:67], v[210:213], v[194:197], v[64:67]
	v_mfma_f32_16x16x32_bf16 v[108:111], v[206:209], v[170:173], v[108:111]
	v_mfma_f32_16x16x32_bf16 v[100:103], v[214:217], v[170:173], v[100:103]
	v_mfma_f32_16x16x32_bf16 v[92:95], v[206:209], v[178:181], v[92:95]
	v_mfma_f32_16x16x32_bf16 v[84:87], v[214:217], v[178:181], v[84:87]
	v_mfma_f32_16x16x32_bf16 v[76:79], v[206:209], v[190:193], v[76:79]
	v_mfma_f32_16x16x32_bf16 v[72:75], v[214:217], v[190:193], v[72:75]
	v_mfma_f32_16x16x32_bf16 v[68:71], v[206:209], v[198:201], v[68:71]
	v_mfma_f32_16x16x32_bf16 v[64:67], v[214:217], v[198:201], v[64:67]
	s_setprio 0
	s_mov_b32 m0, s43
	v_lshl_add_u64 v[182:183], s[36:37], 0, v[128:129]
	s_barrier
	ds_read_b128 v[166:169], v156 offset:16384
	ds_read_b128 v[170:173], v156 offset:17408
	ds_read_b128 v[174:177], v156 offset:18432
	ds_read_b128 v[178:181], v156 offset:19456
	ds_read_b128 v[186:189], v156 offset:20480
	ds_read_b128 v[190:193], v156 offset:21504
	ds_read_b128 v[194:197], v156 offset:22528
	ds_read_b128 v[198:201], v156 offset:23552
	global_load_lds_dwordx4 v[182:183], off
	v_lshl_add_u64 v[218:219], s[36:37], 0, v[130:131]
	s_mov_b32 m0, s44
	s_nop 0
	global_load_lds_dwordx4 v[218:219], off
	s_barrier
	s_waitcnt lgkmcnt(0)
	s_setprio 1
	s_waitcnt lgkmcnt(0)
	v_mfma_f32_16x16x32_bf16 v[60:63], v[138:141], v[166:169], v[60:63]
	v_mfma_f32_16x16x32_bf16 v[56:59], v[146:149], v[166:169], v[56:59]
	v_mfma_f32_16x16x32_bf16 v[52:55], v[138:141], v[174:177], v[52:55]
	v_mfma_f32_16x16x32_bf16 v[48:51], v[146:149], v[174:177], v[48:51]
	v_mfma_f32_16x16x32_bf16 v[40:43], v[138:141], v[186:189], v[40:43]
	v_mfma_f32_16x16x32_bf16 v[32:35], v[146:149], v[186:189], v[32:35]
	v_mfma_f32_16x16x32_bf16 v[24:27], v[138:141], v[194:197], v[24:27]
	v_mfma_f32_16x16x32_bf16 v[16:19], v[146:149], v[194:197], v[16:19]
	v_mfma_f32_16x16x32_bf16 v[60:63], v[142:145], v[170:173], v[60:63]
	v_mfma_f32_16x16x32_bf16 v[56:59], v[162:165], v[170:173], v[56:59]
	v_mfma_f32_16x16x32_bf16 v[52:55], v[142:145], v[178:181], v[52:55]
	v_mfma_f32_16x16x32_bf16 v[48:51], v[162:165], v[178:181], v[48:51]
	v_mfma_f32_16x16x32_bf16 v[40:43], v[142:145], v[190:193], v[40:43]
	v_mfma_f32_16x16x32_bf16 v[32:35], v[162:165], v[190:193], v[32:35]
	v_mfma_f32_16x16x32_bf16 v[24:27], v[142:145], v[198:201], v[24:27]
	v_mfma_f32_16x16x32_bf16 v[16:19], v[162:165], v[198:201], v[16:19]
	s_setprio 0
	s_barrier
; #define PG8_STAGE(bufoff, gbase, voff) do { _Pragma("unroll") for (int _i = 0; _i < 2; ++_i) \
;         __builtin_amdgcn_global_load_lds((const unsigned*)((const char*)(gbase) + (voff)[_i]), (LAS unsigned*)(lds + (bufoff) + ldsw + _i * 8192), 16, 0, 0); } while (0)
; #define PG8_LDA(dst, b, h) do { _Pragma("unroll") for (int m = 0; m < 4; ++m) _Pragma("unroll") for (int k = 0; k < 2; ++k) dst[m][k] = *(const LAS bf16x8*)(lds + PG8_SA(b, h) + aoff + m * 2048 + k * 1024); } while (0)
; #define PG8_LDB(dst, b, h) do { _Pragma("unroll") for (int n = 0; n < 2; ++n) _Pragma("unroll") for (int k = 0; k < 2; ++k) dst[n][k] = *(const LAS bf16x8*)(lds + PG8_SB(b, h) + boff + n * 2048 + k * 1024); } while (0)
; #define PG8_MMA(ai, bj, At, Bt) do { __builtin_amdgcn_s_setprio(1); _Pragma("unroll") for (int m = 0; m < 4; ++m) _Pragma("unroll") for (int n = 0; n < 2; ++n) _Pragma("unroll") for (int k = 0; k < 2; ++k) \
;         acc[ai][bj][m][n] = __builtin_amdgcn_mfma_f32_16x16x32_bf16(Bt[n][k], At[m][k], acc[ai][bj][m][n], 0, 0, 0); __builtin_amdgcn_s_setprio(0); } while (0)
; #define PG8_WAIT_V(n) asm volatile("s_waitcnt vmcnt(" #n ")" ::: "memory")
; #define PG8_WAIT_L(n) asm volatile("s_waitcnt lgkmcnt(" #n ")" ::: "memory")
; #define PG8_BAR __builtin_amdgcn_s_barrier()
; #define PG8_SCHED __builtin_amdgcn_sched_barrier(0)
; template <class Epi, class Sched>
; __device__ __forceinline__ void gemm_phase(LAS unsigned char* lds, const Gemm g, const Sched& S, const Epi& E) {
;     ...
;             PG8_WAIT_V(6); PG8_BAR; PG8_MMA(1, 1, At, B1); PG8_BAR;
;             PG8_LDB(B0, 1, 0); PG8_SCHED; PG8_LDA(At, 1, 0); PG8_STAGE(PG8_SA(0, 1), a2 + hstepA, voffA);
;             PG8_WAIT_L(8); PG8_BAR; PG8_WAIT_L(0); PG8_MMA(0, 0, At, B0); PG8_BAR; PG8_SCHED;
;             PG8_LDB(B1, 1, 1); PG8_STAGE(PG8_SB(1, 0), b3, voffB);
;             PG8_BAR; PG8_WAIT_L(0); if constexpr (!Epi::DIAG) PG8_MMA(0, 1, At, B1); PG8_BAR;
;             PG8_LDA(At, 1, 1); PG8_STAGE(PG8_SA(1, 0), a3, voffA);
;             PG8_BAR; PG8_WAIT_L(0); if constexpr (!Epi::DIAG) PG8_MMA(1, 0, At, B0); PG8_BAR; PG8_SCHED;
	s_add_u32 s76, s34, 0x80000
	s_addc_u32 s77, s35, 0
	s_add_i32 s78, s55, s42
	v_lshl_add_u64 v[138:139], s[76:77], 0, v[128:129]
	s_mov_b32 m0, s78
	s_nop 0
	global_load_lds_dwordx4 v[138:139], off
	v_lshl_add_u64 v[138:139], s[76:77], 0, v[130:131]
	s_add_i32 m0, s78, 0x2000
	s_nop 0
	global_load_lds_dwordx4 v[138:139], off
	s_waitcnt vmcnt(6)
	s_barrier
	s_setprio 1
	v_mfma_f32_16x16x32_bf16 v[44:47], v[202:205], v[166:169], v[44:47]
	v_mfma_f32_16x16x32_bf16 v[36:39], v[210:213], v[166:169], v[36:39]
	v_mfma_f32_16x16x32_bf16 v[28:31], v[202:205], v[174:177], v[28:31]
	v_mfma_f32_16x16x32_bf16 v[20:23], v[210:213], v[174:177], v[20:23]
	v_mfma_f32_16x16x32_bf16 v[12:15], v[202:205], v[186:189], v[12:15]
	v_mfma_f32_16x16x32_bf16 v[8:11], v[210:213], v[186:189], v[8:11]
	v_mfma_f32_16x16x32_bf16 v[4:7], v[202:205], v[194:197], v[4:7]
	v_mfma_f32_16x16x32_bf16 v[0:3], v[210:213], v[194:197], v[0:3]
	v_mfma_f32_16x16x32_bf16 v[44:47], v[206:209], v[170:173], v[44:47]
	v_mfma_f32_16x16x32_bf16 v[36:39], v[214:217], v[170:173], v[36:39]
	v_mfma_f32_16x16x32_bf16 v[28:31], v[206:209], v[178:181], v[28:31]
	v_mfma_f32_16x16x32_bf16 v[20:23], v[214:217], v[178:181], v[20:23]
	v_mfma_f32_16x16x32_bf16 v[12:15], v[206:209], v[190:193], v[12:15]
	v_mfma_f32_16x16x32_bf16 v[8:11], v[214:217], v[190:193], v[8:11]
	v_mfma_f32_16x16x32_bf16 v[4:7], v[206:209], v[198:201], v[4:7]
	v_mfma_f32_16x16x32_bf16 v[0:3], v[214:217], v[198:201], v[0:3]
	s_setprio 0
	s_add_i32 s76, 0, 0x18000
	v_add_u32_e32 v132, s76, v153
	s_barrier
	ds_read_b128 v[138:141], v132
	ds_read_b128 v[142:145], v132 offset:1024
	ds_read_b128 v[146:149], v132 offset:2048
	ds_read_b128 v[162:165], v132 offset:3072
	s_add_u32 s36, s36, 0x80000
	s_addc_u32 s37, s37, 0
	s_mov_b32 m0, s45
	v_lshl_add_u64 v[202:203], s[36:37], 0, v[128:129]
	ds_read_b128 v[166:169], v156 offset:32768
	ds_read_b128 v[170:173], v156 offset:33792
	ds_read_b128 v[174:177], v156 offset:34816
	ds_read_b128 v[178:181], v156 offset:35840
	ds_read_b128 v[186:189], v156 offset:36864
	ds_read_b128 v[190:193], v156 offset:37888
	ds_read_b128 v[194:197], v156 offset:38912
	ds_read_b128 v[198:201], v156 offset:39936
	global_load_lds_dwordx4 v[202:203], off
	v_lshl_add_u64 v[202:203], s[36:37], 0, v[130:131]
	s_mov_b32 m0, s46
	s_nop 0
	global_load_lds_dwordx4 v[202:203], off
	s_waitcnt lgkmcnt(8)
	s_barrier
	s_waitcnt lgkmcnt(0)
	s_setprio 1
	s_waitcnt lgkmcnt(0)
	v_mfma_f32_16x16x32_bf16 v[124:127], v[138:141], v[166:169], v[124:127]
	v_mfma_f32_16x16x32_bf16 v[120:123], v[146:149], v[166:169], v[120:123]
	v_mfma_f32_16x16x32_bf16 v[116:119], v[138:141], v[174:177], v[116:119]
	v_mfma_f32_16x16x32_bf16 v[112:115], v[146:149], v[174:177], v[112:115]
	v_mfma_f32_16x16x32_bf16 v[104:107], v[138:141], v[186:189], v[104:107]
	v_mfma_f32_16x16x32_bf16 v[96:99], v[146:149], v[186:189], v[96:99]
	v_mfma_f32_16x16x32_bf16 v[88:91], v[138:141], v[194:197], v[88:91]
	v_mfma_f32_16x16x32_bf16 v[80:83], v[146:149], v[194:197], v[80:83]
	v_mfma_f32_16x16x32_bf16 v[124:127], v[142:145], v[170:173], v[124:127]
	v_mfma_f32_16x16x32_bf16 v[120:123], v[162:165], v[170:173], v[120:123]
	v_mfma_f32_16x16x32_bf16 v[116:119], v[142:145], v[178:181], v[116:119]
	v_mfma_f32_16x16x32_bf16 v[112:115], v[162:165], v[178:181], v[112:115]
	v_mfma_f32_16x16x32_bf16 v[104:107], v[142:145], v[190:193], v[104:107]
	v_mfma_f32_16x16x32_bf16 v[96:99], v[162:165], v[190:193], v[96:99]
	v_mfma_f32_16x16x32_bf16 v[88:91], v[142:145], v[198:201], v[88:91]
	v_mfma_f32_16x16x32_bf16 v[80:83], v[162:165], v[198:201], v[80:83]
	s_setprio 0
	s_barrier
	s_add_i32 s36, 0, 0x1c000
	s_add_i32 s37, s76, s42
	v_add_u32_e32 v132, s36, v153
	v_lshl_add_u64 v[150:151], v[150:151], 0, s[24:25]
	s_mov_b32 m0, s37
	ds_read_b128 v[202:205], v132
	ds_read_b128 v[206:209], v132 offset:1024
	ds_read_b128 v[210:213], v132 offset:2048
	ds_read_b128 v[214:217], v132 offset:3072
	global_load_lds_dwordx4 v[150:151], off
	v_lshl_add_u64 v[150:151], v[158:159], 0, s[24:25]
	s_add_i32 m0, s37, 0x2000
	s_nop 0
	global_load_lds_dwordx4 v[150:151], off
	s_barrier
	s_waitcnt lgkmcnt(0)
	s_setprio 1
	s_waitcnt lgkmcnt(0)
	v_mfma_f32_16x16x32_bf16 v[108:111], v[202:205], v[166:169], v[108:111]
	v_mfma_f32_16x16x32_bf16 v[100:103], v[210:213], v[166:169], v[100:103]
	v_mfma_f32_16x16x32_bf16 v[92:95], v[202:205], v[174:177], v[92:95]
	v_mfma_f32_16x16x32_bf16 v[84:87], v[210:213], v[174:177], v[84:87]
	v_mfma_f32_16x16x32_bf16 v[76:79], v[202:205], v[186:189], v[76:79]
	v_mfma_f32_16x16x32_bf16 v[72:75], v[210:213], v[186:189], v[72:75]
	v_mfma_f32_16x16x32_bf16 v[68:71], v[202:205], v[194:197], v[68:71]
	v_mfma_f32_16x16x32_bf16 v[64:67], v[210:213], v[194:197], v[64:67]
	v_mfma_f32_16x16x32_bf16 v[108:111], v[206:209], v[170:173], v[108:111]
	v_mfma_f32_16x16x32_bf16 v[100:103], v[214:217], v[170:173], v[100:103]
	v_mfma_f32_16x16x32_bf16 v[92:95], v[206:209], v[178:181], v[92:95]
	v_mfma_f32_16x16x32_bf16 v[84:87], v[214:217], v[178:181], v[84:87]
	v_mfma_f32_16x16x32_bf16 v[76:79], v[206:209], v[190:193], v[76:79]
	v_mfma_f32_16x16x32_bf16 v[72:75], v[214:217], v[190:193], v[72:75]
	v_mfma_f32_16x16x32_bf16 v[68:71], v[206:209], v[198:201], v[68:71]
	v_mfma_f32_16x16x32_bf16 v[64:67], v[214:217], v[198:201], v[64:67]
	s_setprio 0
	s_mov_b32 m0, s50
	v_lshl_add_u64 v[150:151], v[182:183], 0, s[24:25]
	s_barrier
	ds_read_b128 v[166:169], v156 offset:49152
	ds_read_b128 v[170:173], v156 offset:50176
	ds_read_b128 v[174:177], v156 offset:51200
	ds_read_b128 v[178:181], v156 offset:52224
	ds_read_b128 v[186:189], v156 offset:53248
	ds_read_b128 v[190:193], v156 offset:54272
	ds_read_b128 v[194:197], v156 offset:55296
	ds_read_b128 v[198:201], v156 offset:56320
	global_load_lds_dwordx4 v[150:151], off
	v_lshl_add_u64 v[150:151], v[218:219], 0, s[24:25]
	s_mov_b32 m0, s51
	s_nop 0
	global_load_lds_dwordx4 v[150:151], off
	s_barrier
; #define PG8_STAGE(bufoff, gbase, voff) do { _Pragma("unroll") for (int _i = 0; _i < 2; ++_i) \
;         __builtin_amdgcn_global_load_lds((const unsigned*)((const char*)(gbase) + (voff)[_i]), (LAS unsigned*)(lds + (bufoff) + ldsw + _i * 8192), 16, 0, 0); } while (0)
; #define PG8_MMA(ai, bj, At, Bt) do { __builtin_amdgcn_s_setprio(1); _Pragma("unroll") for (int m = 0; m < 4; ++m) _Pragma("unroll") for (int n = 0; n < 2; ++n) _Pragma("unroll") for (int k = 0; k < 2; ++k) \
;         acc[ai][bj][m][n] = __builtin_amdgcn_mfma_f32_16x16x32_bf16(Bt[n][k], At[m][k], acc[ai][bj][m][n], 0, 0, 0); __builtin_amdgcn_s_setprio(0); } while (0)
; template <class Epi, class Sched>
; __device__ __forceinline__ void gemm_phase(LAS unsigned char* lds, const Gemm g, const Sched& S, const Epi& E) {
;     ...
;             PG8_STAGE(PG8_SB(1, 1), b3 + hstepB, voffB);
;             PG8_WAIT_V(6); PG8_BAR; PG8_MMA(1, 1, At, B1); PG8_BAR;
;         }
;     __device__ __forceinline__ void operator()(const Acc& acc, const Unit& u, int wr, int wc, int fr, int fq) const {
;         const int row0 = u.pm * BM + wr * 64 + fr, col0 = u.pn * BM + wc * 32 + 4 * fq;
;         if (u.piece >= 0) {
;             float* pb = PB + (size_t)u.piece * TS * DM;
; #pragma unroll
;             for (int ai = 0; ai < 2; ++ai)
; #pragma unroll
;                 for (int m = 0; m < 4; ++m) { float* orow = pb + (size_t)(row0 + ai * HALF + m * 16 - TP) * DM;
; #pragma unroll
;                     for (int bj = 0; bj < 2; ++bj)
; #pragma unroll
;                         for (int n = 0; n < 2; ++n) *(f32x4*)(orow + col0 + bj * HALF + n * 16) = acc[ai][bj][m][n]; }
;             return;
;         }
; #pragma unroll
;         for (int ai = 0; ai < 2; ++ai)
; #pragma unroll
;             for (int m = 0; m < 4; ++m) { const int row = row0 + ai * HALF + m * 16; const int b = bidx_of_row(row);
;                 const float* xr = (row < TP) ? x0p + (size_t)row * DM : x0s + (size_t)(row - TP) * DM; const float* gr = gate + (size_t)b * MODW; float* orow = X1 + (size_t)row * DM;
; #pragma unroll
;                 for (int bj = 0; bj < 2; ++bj)
; #pragma unroll
;                     for (int n = 0; n < 2; ++n) { const int c = col0 + bj * HALF + n * 16; const f32x4 xv = *(const f32x4*)(xr + c), gv = *(const f32x4*)(gr + c);
;                         *(f32x4*)(orow + c) = xv + gv * acc[ai][bj][m][n]; } }
	s_waitcnt lgkmcnt(0)
	s_setprio 1
	s_waitcnt lgkmcnt(0)
	v_mfma_f32_16x16x32_bf16 v[60:63], v[138:141], v[166:169], v[60:63]
	v_mfma_f32_16x16x32_bf16 v[56:59], v[146:149], v[166:169], v[56:59]
	v_mfma_f32_16x16x32_bf16 v[52:55], v[138:141], v[174:177], v[52:55]
	v_mfma_f32_16x16x32_bf16 v[48:51], v[146:149], v[174:177], v[48:51]
	v_mfma_f32_16x16x32_bf16 v[40:43], v[138:141], v[186:189], v[40:43]
	v_mfma_f32_16x16x32_bf16 v[32:35], v[146:149], v[186:189], v[32:35]
	v_mfma_f32_16x16x32_bf16 v[24:27], v[138:141], v[194:197], v[24:27]
	v_mfma_f32_16x16x32_bf16 v[16:19], v[146:149], v[194:197], v[16:19]
	v_mfma_f32_16x16x32_bf16 v[60:63], v[142:145], v[170:173], v[60:63]
	v_mfma_f32_16x16x32_bf16 v[56:59], v[162:165], v[170:173], v[56:59]
	v_mfma_f32_16x16x32_bf16 v[52:55], v[142:145], v[178:181], v[52:55]
	v_mfma_f32_16x16x32_bf16 v[48:51], v[162:165], v[178:181], v[48:51]
	v_mfma_f32_16x16x32_bf16 v[40:43], v[142:145], v[190:193], v[40:43]
	v_mfma_f32_16x16x32_bf16 v[32:35], v[162:165], v[190:193], v[32:35]
	v_mfma_f32_16x16x32_bf16 v[24:27], v[142:145], v[198:201], v[24:27]
	v_mfma_f32_16x16x32_bf16 v[16:19], v[162:165], v[198:201], v[16:19]
	s_setprio 0
	s_barrier
	s_add_u32 s34, s34, 0x80080
	s_addc_u32 s35, s35, 0
	s_add_i32 s36, s36, s42
	v_lshl_add_u64 v[138:139], s[34:35], 0, v[128:129]
	s_mov_b32 m0, s36
	s_nop 0
	global_load_lds_dwordx4 v[138:139], off
	v_lshl_add_u64 v[138:139], s[34:35], 0, v[130:131]
	s_add_i32 m0, s36, 0x2000
	s_nop 0
	global_load_lds_dwordx4 v[138:139], off
	s_waitcnt vmcnt(6)
	s_barrier
	s_setprio 1
	v_mfma_f32_16x16x32_bf16 v[44:47], v[202:205], v[166:169], v[44:47]
	v_mfma_f32_16x16x32_bf16 v[36:39], v[210:213], v[166:169], v[36:39]
	v_mfma_f32_16x16x32_bf16 v[28:31], v[202:205], v[174:177], v[28:31]
	v_mfma_f32_16x16x32_bf16 v[20:23], v[210:213], v[174:177], v[20:23]
	v_mfma_f32_16x16x32_bf16 v[12:15], v[202:205], v[186:189], v[12:15]
	v_mfma_f32_16x16x32_bf16 v[8:11], v[210:213], v[186:189], v[8:11]
	v_mfma_f32_16x16x32_bf16 v[4:7], v[202:205], v[194:197], v[4:7]
	v_mfma_f32_16x16x32_bf16 v[0:3], v[210:213], v[194:197], v[0:3]
	v_mfma_f32_16x16x32_bf16 v[44:47], v[206:209], v[170:173], v[44:47]
	v_mfma_f32_16x16x32_bf16 v[36:39], v[214:217], v[170:173], v[36:39]
	v_mfma_f32_16x16x32_bf16 v[28:31], v[206:209], v[178:181], v[28:31]
	v_mfma_f32_16x16x32_bf16 v[20:23], v[214:217], v[178:181], v[20:23]
	v_mfma_f32_16x16x32_bf16 v[12:15], v[206:209], v[190:193], v[12:15]
	v_mfma_f32_16x16x32_bf16 v[8:11], v[214:217], v[190:193], v[8:11]
	v_mfma_f32_16x16x32_bf16 v[4:7], v[206:209], v[198:201], v[4:7]
	v_mfma_f32_16x16x32_bf16 v[0:3], v[214:217], v[198:201], v[0:3]
	s_setprio 0
	s_add_u32 s80, s80, 0x100
	s_and_b32 s80, s80, 0xfff
	s_cmp_ge_u32 s75, s67
	s_mov_b32 s34, s75
	s_barrier
	s_cbranch_scc0 .LBB0_1653
	s_lshl_b32 s13, s69, 8
	s_add_i32 s13, s13, s52
	v_or_b32_e32 v138, s13, v152
	v_lshl_or_b32 v142, s68, 8, v154
	s_cmp_gt_i32 s16, -1
	v_add_u32_e32 v140, 0xffffe000, v138
	s_mov_b64 s[6:7], -1
	s_cbranch_scc1 .LBB0_1688
	v_cmp_gt_i32_e32 vcc, s47, v138
	v_cmp_lt_i32_e64 s[6:7], s56, v138
	s_and_saveexec_b64 s[34:35], s[6:7]
	s_xor_b64 s[6:7], exec, s[34:35]
	v_mov_b32_e32 v141, v133
	v_lshlrev_b64 v[144:145], 13, v[140:141]
	v_mov_b32_e32 v139, v133
	v_lshl_add_u64 v[148:149], s[10:11], 0, v[144:145]
	v_lshlrev_b64 v[146:147], 13, v[138:139]
	s_andn2_saveexec_b64 s[6:7], s[6:7]
	v_ashrrev_i32_e32 v139, 31, v138
	v_lshlrev_b64 v[146:147], 13, v[138:139]
	v_lshl_add_u64 v[148:149], s[8:9], 0, v[146:147]
	s_or_b64 exec, exec, s[6:7]
	s_ashr_i32 s13, s13, 11
	v_lshrrev_b32_e32 v132, 2, v140
	v_or_b32_e32 v132, 4, v132
	v_mov_b32_e32 v139, s13
	v_cndmask_b32_e32 v132, v132, v139, vcc
	v_mov_b64_e32 v[144:145], s[22:23]
	v_ashrrev_i32_e32 v143, 31, v142
	v_mad_i64_i32 v[158:159], s[6:7], v132, s54, v[144:145]
	v_lshlrev_b64 v[144:145], 2, v[142:143]
	v_lshl_add_u64 v[166:167], v[148:149], 0, v[144:145]
	v_lshl_add_u64 v[158:159], v[158:159], 0, v[144:145]
	global_load_dwordx4 v[186:189], v[166:167], off
	global_load_dwordx4 v[202:205], v[158:159], off
	global_load_dwordx4 v[190:193], v[166:167], off offset:64
	global_load_dwordx4 v[206:209], v[158:159], off offset:64
	global_load_dwordx4 v[194:197], v[166:167], off offset:512
	global_load_dwordx4 v[210:213], v[158:159], off offset:512
	global_load_dwordx4 v[198:201], v[166:167], off offset:576
	global_load_dwordx4 v[214:217], v[158:159], off offset:576
	v_lshl_add_u64 v[146:147], s[26:27], 0, v[146:147]
	v_lshl_add_u64 v[168:169], v[146:147], 0, v[144:145]
	v_add_u32_e32 v132, 0xffffe010, v138
	s_waitcnt vmcnt(6)
	v_pk_fma_f32 v[188:189], v[126:127], v[204:205], v[188:189]
	v_pk_fma_f32 v[186:187], v[124:125], v[202:203], v[186:187]
	global_store_dwordx4 v[168:169], v[186:189], off
	v_or_b32_e32 v150, 16, v138
	v_cmp_gt_i32_e32 vcc, s47, v150
	v_cmp_lt_i32_e64 s[6:7], s56, v150
	s_waitcnt vmcnt(5)
	v_pk_fma_f32 v[192:193], v[122:123], v[208:209], v[192:193]
	v_pk_fma_f32 v[190:191], v[120:121], v[206:207], v[190:191]
	global_store_dwordx4 v[168:169], v[190:193], off offset:64
	s_waitcnt vmcnt(4)
	v_pk_fma_f32 v[196:197], v[110:111], v[212:213], v[196:197]
	v_pk_fma_f32 v[194:195], v[108:109], v[210:211], v[194:195]
	global_store_dwordx4 v[168:169], v[194:197], off offset:512
	s_waitcnt vmcnt(3)
;     __device__ __forceinline__ void operator()(const Acc& acc, const Unit& u, int wr, int wc, int fr, int fq) const {
;     ...
; #pragma unroll
;         for (int ai = 0; ai < 2; ++ai)
; #pragma unroll
;             for (int m = 0; m < 4; ++m) { const int row = row0 + ai * HALF + m * 16; const int b = bidx_of_row(row);
;                 const float* xr = (row < TP) ? x0p + (size_t)row * DM : x0s + (size_t)(row - TP) * DM; const float* gr = gate + (size_t)b * MODW; float* orow = X1 + (size_t)row * DM;
; #pragma unroll
;                 for (int bj = 0; bj < 2; ++bj)
; #pragma unroll
;                     for (int n = 0; n < 2; ++n) { const int c = col0 + bj * HALF + n * 16; const f32x4 xv = *(const f32x4*)(xr + c), gv = *(const f32x4*)(gr + c);
;                         *(f32x4*)(orow + c) = xv + gv * acc[ai][bj][m][n]; } }
	v_pk_fma_f32 v[200:201], v[102:103], v[216:217], v[200:201]
	v_pk_fma_f32 v[198:199], v[100:101], v[214:215], v[198:199]
	global_store_dwordx4 v[168:169], v[198:201], off offset:576
	s_and_saveexec_b64 s[34:35], s[6:7]
	s_xor_b64 s[6:7], exec, s[34:35]
	v_lshlrev_b64 v[146:147], 13, v[132:133]
	v_mov_b32_e32 v151, v133
	v_lshl_add_u64 v[148:149], s[10:11], 0, v[146:147]
	v_lshlrev_b64 v[146:147], 13, v[150:151]
	s_andn2_saveexec_b64 s[6:7], s[6:7]
	v_ashrrev_i32_e32 v151, 31, v150
	v_lshlrev_b64 v[146:147], 13, v[150:151]
	v_lshl_add_u64 v[148:149], s[8:9], 0, v[146:147]
	s_or_b64 exec, exec, s[6:7]
	v_lshrrev_b32_e32 v132, 2, v132
	v_add_u32_e32 v132, 4, v132
	v_mov_b32_e32 v139, s13
	v_cndmask_b32_e32 v132, v132, v139, vcc
	v_mov_b64_e32 v[150:151], s[22:23]
	v_mad_i64_i32 v[158:159], s[6:7], v132, s54, v[150:151]
	v_lshl_add_u64 v[166:167], v[148:149], 0, v[144:145]
	v_lshl_add_u64 v[158:159], v[158:159], 0, v[144:145]
	global_load_dwordx4 v[186:189], v[166:167], off
	global_load_dwordx4 v[202:205], v[158:159], off
	global_load_dwordx4 v[190:193], v[166:167], off offset:64
	global_load_dwordx4 v[206:209], v[158:159], off offset:64
	global_load_dwordx4 v[194:197], v[166:167], off offset:512
	global_load_dwordx4 v[210:213], v[158:159], off offset:512
	global_load_dwordx4 v[198:201], v[166:167], off offset:576
	global_load_dwordx4 v[214:217], v[158:159], off offset:576
	v_lshl_add_u64 v[146:147], s[26:27], 0, v[146:147]
	v_lshl_add_u64 v[168:169], v[146:147], 0, v[144:145]
	v_add_u32_e32 v132, 0xffffe020, v138
	s_waitcnt vmcnt(6)
	v_pk_fma_f32 v[188:189], v[118:119], v[204:205], v[188:189]
	v_pk_fma_f32 v[186:187], v[116:117], v[202:203], v[186:187]
	global_store_dwordx4 v[168:169], v[186:189], off
	v_or_b32_e32 v150, 32, v138
	v_cmp_gt_i32_e32 vcc, s47, v150
	v_cmp_lt_i32_e64 s[6:7], s56, v150
	s_waitcnt vmcnt(5)
	v_pk_fma_f32 v[192:193], v[114:115], v[208:209], v[192:193]
	v_pk_fma_f32 v[190:191], v[112:113], v[206:207], v[190:191]
	global_store_dwordx4 v[168:169], v[190:193], off offset:64
	s_waitcnt vmcnt(4)
	v_pk_fma_f32 v[196:197], v[94:95], v[212:213], v[196:197]
	v_pk_fma_f32 v[194:195], v[92:93], v[210:211], v[194:195]
	global_store_dwordx4 v[168:169], v[194:197], off offset:512
	s_waitcnt vmcnt(3)
	v_pk_fma_f32 v[200:201], v[86:87], v[216:217], v[200:201]
	v_pk_fma_f32 v[198:199], v[84:85], v[214:215], v[198:199]
	global_store_dwordx4 v[168:169], v[198:201], off offset:576
	s_and_saveexec_b64 s[34:35], s[6:7]
	s_xor_b64 s[6:7], exec, s[34:35]
	v_lshlrev_b64 v[146:147], 13, v[132:133]
	v_mov_b32_e32 v151, v133
	v_lshl_add_u64 v[148:149], s[10:11], 0, v[146:147]
	v_lshlrev_b64 v[146:147], 13, v[150:151]
	s_andn2_saveexec_b64 s[6:7], s[6:7]
	v_ashrrev_i32_e32 v151, 31, v150
	v_lshlrev_b64 v[146:147], 13, v[150:151]
	v_lshl_add_u64 v[148:149], s[8:9], 0, v[146:147]
	s_or_b64 exec, exec, s[6:7]
	v_lshrrev_b32_e32 v132, 2, v132
	v_or_b32_e32 v132, 4, v132
	v_mov_b32_e32 v139, s13
	v_cndmask_b32_e32 v132, v132, v139, vcc
	v_mov_b64_e32 v[150:151], s[22:23]
	v_mad_i64_i32 v[158:159], s[6:7], v132, s54, v[150:151]
	v_lshl_add_u64 v[166:167], v[148:149], 0, v[144:145]
	v_lshl_add_u64 v[158:159], v[158:159], 0, v[144:145]
	global_load_dwordx4 v[186:189], v[166:167], off
	global_load_dwordx4 v[202:205], v[158:159], off
	global_load_dwordx4 v[190:193], v[166:167], off offset:64
	global_load_dwordx4 v[206:209], v[158:159], off offset:64
	global_load_dwordx4 v[194:197], v[166:167], off offset:512
	global_load_dwordx4 v[210:213], v[158:159], off offset:512
	global_load_dwordx4 v[198:201], v[166:167], off offset:576
	global_load_dwordx4 v[214:217], v[158:159], off offset:576
	v_lshl_add_u64 v[146:147], s[26:27], 0, v[146:147]
	v_lshl_add_u64 v[168:169], v[146:147], 0, v[144:145]
	v_add_u32_e32 v132, 0xffffe030, v138
	s_waitcnt vmcnt(6)
	v_pk_fma_f32 v[188:189], v[106:107], v[204:205], v[188:189]
	v_pk_fma_f32 v[186:187], v[104:105], v[202:203], v[186:187]
	global_store_dwordx4 v[168:169], v[186:189], off
	v_or_b32_e32 v150, 48, v138
	v_cmp_gt_i32_e32 vcc, s47, v150
	v_cmp_lt_i32_e64 s[6:7], s56, v150
	s_waitcnt vmcnt(5)
	v_pk_fma_f32 v[192:193], v[98:99], v[208:209], v[192:193]
	v_pk_fma_f32 v[190:191], v[96:97], v[206:207], v[190:191]
	global_store_dwordx4 v[168:169], v[190:193], off offset:64
	s_waitcnt vmcnt(4)
	v_pk_fma_f32 v[196:197], v[78:79], v[212:213], v[196:197]
	v_pk_fma_f32 v[194:195], v[76:77], v[210:211], v[194:195]
	global_store_dwordx4 v[168:169], v[194:197], off offset:512
	s_waitcnt vmcnt(3)
	v_pk_fma_f32 v[200:201], v[74:75], v[216:217], v[200:201]
	v_pk_fma_f32 v[198:199], v[72:73], v[214:215], v[198:199]
	global_store_dwordx4 v[168:169], v[198:201], off offset:576
	s_and_saveexec_b64 s[34:35], s[6:7]
	s_xor_b64 s[6:7], exec, s[34:35]
	v_lshlrev_b64 v[146:147], 13, v[132:133]
	v_mov_b32_e32 v151, v133
	v_lshl_add_u64 v[148:149], s[10:11], 0, v[146:147]
	v_lshlrev_b64 v[146:147], 13, v[150:151]
	s_andn2_saveexec_b64 s[6:7], s[6:7]
	v_ashrrev_i32_e32 v151, 31, v150
	v_lshlrev_b64 v[146:147], 13, v[150:151]
	v_lshl_add_u64 v[148:149], s[8:9], 0, v[146:147]
	s_or_b64 exec, exec, s[6:7]
	v_lshrrev_b32_e32 v132, 2, v132
	v_add_u32_e32 v132, 4, v132
	v_mov_b32_e32 v139, s13
	v_cndmask_b32_e32 v132, v132, v139, vcc
	v_mov_b64_e32 v[150:151], s[22:23]
	v_mad_i64_i32 v[158:159], s[6:7], v132, s54, v[150:151]
	v_lshl_add_u64 v[166:167], v[148:149], 0, v[144:145]
	v_lshl_add_u64 v[158:159], v[158:159], 0, v[144:145]
	global_load_dwordx4 v[186:189], v[166:167], off
	global_load_dwordx4 v[202:205], v[158:159], off
	global_load_dwordx4 v[190:193], v[166:167], off offset:64
	global_load_dwordx4 v[206:209], v[158:159], off offset:64
	global_load_dwordx4 v[194:197], v[166:167], off offset:512
	global_load_dwordx4 v[210:213], v[158:159], off offset:512
	global_load_dwordx4 v[198:201], v[166:167], off offset:576
	global_load_dwordx4 v[214:217], v[158:159], off offset:576
	v_lshl_add_u64 v[146:147], s[26:27], 0, v[146:147]
	v_lshl_add_u64 v[168:169], v[146:147], 0, v[144:145]
	v_cmp_gt_i32_e32 vcc, s57, v138
	v_cmp_lt_i32_e64 s[6:7], s58, v138
	v_add_u32_e32 v132, 0xffffe080, v138
	s_waitcnt vmcnt(6)
;     __device__ __forceinline__ void operator()(const Acc& acc, const Unit& u, int wr, int wc, int fr, int fq) const {
;     ...
; #pragma unroll
;         for (int ai = 0; ai < 2; ++ai)
; #pragma unroll
;             for (int m = 0; m < 4; ++m) { const int row = row0 + ai * HALF + m * 16; const int b = bidx_of_row(row);
;                 const float* xr = (row < TP) ? x0p + (size_t)row * DM : x0s + (size_t)(row - TP) * DM; const float* gr = gate + (size_t)b * MODW; float* orow = X1 + (size_t)row * DM;
; #pragma unroll
;                 for (int bj = 0; bj < 2; ++bj)
; #pragma unroll
;                     for (int n = 0; n < 2; ++n) { const int c = col0 + bj * HALF + n * 16; const f32x4 xv = *(const f32x4*)(xr + c), gv = *(const f32x4*)(gr + c);
;                         *(f32x4*)(orow + c) = xv + gv * acc[ai][bj][m][n]; } }
	v_pk_fma_f32 v[188:189], v[90:91], v[204:205], v[188:189]
	v_pk_fma_f32 v[186:187], v[88:89], v[202:203], v[186:187]
	global_store_dwordx4 v[168:169], v[186:189], off
	s_waitcnt vmcnt(5)
	v_pk_fma_f32 v[192:193], v[82:83], v[208:209], v[192:193]
	v_pk_fma_f32 v[190:191], v[80:81], v[206:207], v[190:191]
	global_store_dwordx4 v[168:169], v[190:193], off offset:64
	s_waitcnt vmcnt(4)
	v_pk_fma_f32 v[196:197], v[70:71], v[212:213], v[196:197]
	v_pk_fma_f32 v[194:195], v[68:69], v[210:211], v[194:195]
	global_store_dwordx4 v[168:169], v[194:197], off offset:512
	v_add_u32_e32 v146, 0x80, v138
	s_waitcnt vmcnt(3)
	v_pk_fma_f32 v[200:201], v[66:67], v[216:217], v[200:201]
	v_pk_fma_f32 v[198:199], v[64:65], v[214:215], v[198:199]
	global_store_dwordx4 v[168:169], v[198:201], off offset:576
	s_and_saveexec_b64 s[34:35], s[6:7]
	s_xor_b64 s[6:7], exec, s[34:35]
	v_lshlrev_b64 v[148:149], 13, v[132:133]
	v_mov_b32_e32 v147, v133
	v_lshl_add_u64 v[150:151], s[10:11], 0, v[148:149]
	v_lshlrev_b64 v[148:149], 13, v[146:147]
	s_andn2_saveexec_b64 s[6:7], s[6:7]
	v_ashrrev_i32_e32 v147, 31, v146
	v_lshlrev_b64 v[148:149], 13, v[146:147]
	v_lshl_add_u64 v[150:151], s[8:9], 0, v[148:149]
	s_or_b64 exec, exec, s[6:7]
	v_lshrrev_b32_e32 v132, 2, v132
	v_ashrrev_i32_e32 v139, 11, v146
	v_or_b32_e32 v132, 4, v132
	v_cndmask_b32_e32 v132, v132, v139, vcc
	v_mov_b64_e32 v[146:147], s[22:23]
	v_mad_i64_i32 v[146:147], s[6:7], v132, s54, v[146:147]
	v_lshl_add_u64 v[150:151], v[150:151], 0, v[144:145]
	v_lshl_add_u64 v[158:159], v[146:147], 0, v[144:145]
	global_load_dwordx4 v[186:189], v[150:151], off
	global_load_dwordx4 v[202:205], v[158:159], off
	global_load_dwordx4 v[190:193], v[150:151], off offset:64
	global_load_dwordx4 v[206:209], v[158:159], off offset:64
	global_load_dwordx4 v[194:197], v[150:151], off offset:512
	global_load_dwordx4 v[210:213], v[158:159], off offset:512
	global_load_dwordx4 v[198:201], v[150:151], off offset:576
	global_load_dwordx4 v[214:217], v[158:159], off offset:576
	v_lshl_add_u64 v[146:147], s[26:27], 0, v[148:149]
	v_lshl_add_u64 v[170:171], v[146:147], 0, v[144:145]
	v_cmp_gt_i32_e32 vcc, s59, v138
	v_cmp_lt_i32_e64 s[6:7], s60, v138
	v_add_u32_e32 v132, 0xffffe090, v138
	s_waitcnt vmcnt(6)
	v_pk_fma_f32 v[148:149], v[62:63], v[204:205], v[188:189]
	v_pk_fma_f32 v[146:147], v[60:61], v[202:203], v[186:187]
	global_store_dwordx4 v[170:171], v[146:149], off
	s_waitcnt vmcnt(5)
	v_pk_fma_f32 v[192:193], v[58:59], v[208:209], v[192:193]
	v_pk_fma_f32 v[190:191], v[56:57], v[206:207], v[190:191]
	global_store_dwordx4 v[170:171], v[190:193], off offset:64
	s_waitcnt vmcnt(4)
	v_pk_fma_f32 v[196:197], v[46:47], v[212:213], v[196:197]
	v_pk_fma_f32 v[194:195], v[44:45], v[210:211], v[194:195]
	global_store_dwordx4 v[170:171], v[194:197], off offset:512
	v_add_u32_e32 v150, 0x90, v138
	s_waitcnt vmcnt(3)
	v_pk_fma_f32 v[200:201], v[38:39], v[216:217], v[200:201]
	v_pk_fma_f32 v[198:199], v[36:37], v[214:215], v[198:199]
	global_store_dwordx4 v[170:171], v[198:201], off offset:576
	s_and_saveexec_b64 s[34:35], s[6:7]
	s_xor_b64 s[6:7], exec, s[34:35]
	v_lshlrev_b64 v[146:147], 13, v[132:133]
	v_mov_b32_e32 v151, v133
	v_lshl_add_u64 v[148:149], s[10:11], 0, v[146:147]
	v_lshlrev_b64 v[146:147], 13, v[150:151]
	s_andn2_saveexec_b64 s[6:7], s[6:7]
	v_ashrrev_i32_e32 v151, 31, v150
	v_lshlrev_b64 v[146:147], 13, v[150:151]
	v_lshl_add_u64 v[148:149], s[8:9], 0, v[146:147]
	s_or_b64 exec, exec, s[6:7]
	v_lshrrev_b32_e32 v132, 2, v132
	v_add_u32_e32 v132, 4, v132
	v_cndmask_b32_e32 v132, v132, v139, vcc
	v_mov_b64_e32 v[150:151], s[22:23]
	v_mad_i64_i32 v[158:159], s[6:7], v132, s54, v[150:151]
	v_lshl_add_u64 v[166:167], v[148:149], 0, v[144:145]
	v_lshl_add_u64 v[158:159], v[158:159], 0, v[144:145]
	global_load_dwordx4 v[186:189], v[166:167], off
	global_load_dwordx4 v[202:205], v[158:159], off
	global_load_dwordx4 v[190:193], v[166:167], off offset:64
	global_load_dwordx4 v[206:209], v[158:159], off offset:64
	global_load_dwordx4 v[194:197], v[166:167], off offset:512
	global_load_dwordx4 v[210:213], v[158:159], off offset:512
	global_load_dwordx4 v[198:201], v[166:167], off offset:576
	global_load_dwordx4 v[214:217], v[158:159], off offset:576
	v_lshl_add_u64 v[146:147], s[26:27], 0, v[146:147]
	v_lshl_add_u64 v[168:169], v[146:147], 0, v[144:145]
	v_cmp_gt_i32_e32 vcc, s61, v138
	v_cmp_lt_i32_e64 s[6:7], s62, v138
	v_add_u32_e32 v132, 0xffffe0a0, v138
	s_waitcnt vmcnt(6)
	v_pk_fma_f32 v[188:189], v[54:55], v[204:205], v[188:189]
	v_pk_fma_f32 v[186:187], v[52:53], v[202:203], v[186:187]
	global_store_dwordx4 v[168:169], v[186:189], off
	v_add_u32_e32 v150, 0xa0, v138
	s_waitcnt vmcnt(5)
;     __device__ __forceinline__ void operator()(const Acc& acc, const Unit& u, int wr, int wc, int fr, int fq) const {
;     ...
; #pragma unroll
;         for (int ai = 0; ai < 2; ++ai)
; #pragma unroll
;             for (int m = 0; m < 4; ++m) { const int row = row0 + ai * HALF + m * 16; const int b = bidx_of_row(row);
;                 const float* xr = (row < TP) ? x0p + (size_t)row * DM : x0s + (size_t)(row - TP) * DM; const float* gr = gate + (size_t)b * MODW; float* orow = X1 + (size_t)row * DM;
; #pragma unroll
;                 for (int bj = 0; bj < 2; ++bj)
; #pragma unroll
;                     for (int n = 0; n < 2; ++n) { const int c = col0 + bj * HALF + n * 16; const f32x4 xv = *(const f32x4*)(xr + c), gv = *(const f32x4*)(gr + c);
;                         *(f32x4*)(orow + c) = xv + gv * acc[ai][bj][m][n]; } }
	v_pk_fma_f32 v[192:193], v[50:51], v[208:209], v[192:193]
	v_pk_fma_f32 v[190:191], v[48:49], v[206:207], v[190:191]
	global_store_dwordx4 v[168:169], v[190:193], off offset:64
	s_waitcnt vmcnt(4)
	v_pk_fma_f32 v[196:197], v[30:31], v[212:213], v[196:197]
	v_pk_fma_f32 v[194:195], v[28:29], v[210:211], v[194:195]
	global_store_dwordx4 v[168:169], v[194:197], off offset:512
	s_waitcnt vmcnt(3)
	v_pk_fma_f32 v[200:201], v[22:23], v[216:217], v[200:201]
	v_pk_fma_f32 v[198:199], v[20:21], v[214:215], v[198:199]
	global_store_dwordx4 v[168:169], v[198:201], off offset:576
	s_and_saveexec_b64 s[34:35], s[6:7]
	s_xor_b64 s[6:7], exec, s[34:35]
	v_lshlrev_b64 v[146:147], 13, v[132:133]
	v_mov_b32_e32 v151, v133
	v_lshl_add_u64 v[148:149], s[10:11], 0, v[146:147]
	v_lshlrev_b64 v[146:147], 13, v[150:151]
	s_andn2_saveexec_b64 s[6:7], s[6:7]
	v_ashrrev_i32_e32 v151, 31, v150
	v_lshlrev_b64 v[146:147], 13, v[150:151]
	v_lshl_add_u64 v[148:149], s[8:9], 0, v[146:147]
	s_or_b64 exec, exec, s[6:7]
	v_lshrrev_b32_e32 v132, 2, v132
	v_or_b32_e32 v132, 4, v132
	v_cndmask_b32_e32 v132, v132, v139, vcc
	v_mov_b64_e32 v[150:151], s[22:23]
	v_mad_i64_i32 v[158:159], s[6:7], v132, s54, v[150:151]
	v_lshl_add_u64 v[166:167], v[148:149], 0, v[144:145]
	v_lshl_add_u64 v[158:159], v[158:159], 0, v[144:145]
	global_load_dwordx4 v[186:189], v[166:167], off
	global_load_dwordx4 v[202:205], v[158:159], off
	global_load_dwordx4 v[190:193], v[166:167], off offset:64
	global_load_dwordx4 v[206:209], v[158:159], off offset:64
	global_load_dwordx4 v[194:197], v[166:167], off offset:512
	global_load_dwordx4 v[210:213], v[158:159], off offset:512
	global_load_dwordx4 v[198:201], v[166:167], off offset:576
	global_load_dwordx4 v[214:217], v[158:159], off offset:576
	v_lshl_add_u64 v[146:147], s[26:27], 0, v[146:147]
	v_lshl_add_u64 v[168:169], v[146:147], 0, v[144:145]
	v_cmp_gt_i32_e32 vcc, s63, v138
	v_cmp_lt_i32_e64 s[6:7], s64, v138
	v_add_u32_e32 v132, 0xffffe0b0, v138
	s_waitcnt vmcnt(6)
	v_pk_fma_f32 v[188:189], v[42:43], v[204:205], v[188:189]
	v_pk_fma_f32 v[186:187], v[40:41], v[202:203], v[186:187]
	global_store_dwordx4 v[168:169], v[186:189], off
	v_add_u32_e32 v150, 0xb0, v138
	s_waitcnt vmcnt(5)
	v_pk_fma_f32 v[192:193], v[34:35], v[208:209], v[192:193]
	v_pk_fma_f32 v[190:191], v[32:33], v[206:207], v[190:191]
	global_store_dwordx4 v[168:169], v[190:193], off offset:64
	s_waitcnt vmcnt(4)
	v_pk_fma_f32 v[196:197], v[14:15], v[212:213], v[196:197]
	v_pk_fma_f32 v[194:195], v[12:13], v[210:211], v[194:195]
	global_store_dwordx4 v[168:169], v[194:197], off offset:512
	s_waitcnt vmcnt(3)
	v_pk_fma_f32 v[200:201], v[10:11], v[216:217], v[200:201]
	v_pk_fma_f32 v[198:199], v[8:9], v[214:215], v[198:199]
	global_store_dwordx4 v[168:169], v[198:201], off offset:576
	s_and_saveexec_b64 s[34:35], s[6:7]
	s_xor_b64 s[6:7], exec, s[34:35]
	v_lshlrev_b64 v[146:147], 13, v[132:133]
	v_mov_b32_e32 v151, v133
	v_lshl_add_u64 v[148:149], s[10:11], 0, v[146:147]
	v_lshlrev_b64 v[146:147], 13, v[150:151]
	s_andn2_saveexec_b64 s[6:7], s[6:7]
	v_ashrrev_i32_e32 v151, 31, v150
	v_lshlrev_b64 v[146:147], 13, v[150:151]
	v_lshl_add_u64 v[148:149], s[8:9], 0, v[146:147]
	s_or_b64 exec, exec, s[6:7]
	v_lshrrev_b32_e32 v132, 2, v132
	v_add_u32_e32 v132, 4, v132
	v_cndmask_b32_e32 v132, v132, v139, vcc
	v_mov_b64_e32 v[150:151], s[22:23]
	v_mad_i64_i32 v[158:159], s[6:7], v132, s54, v[150:151]
	v_lshl_add_u64 v[166:167], v[148:149], 0, v[144:145]
	v_lshl_add_u64 v[158:159], v[158:159], 0, v[144:145]
	global_load_dwordx4 v[186:189], v[166:167], off
	global_load_dwordx4 v[202:205], v[158:159], off
	global_load_dwordx4 v[190:193], v[166:167], off offset:64
	global_load_dwordx4 v[206:209], v[158:159], off offset:64
	global_load_dwordx4 v[194:197], v[166:167], off offset:512
	global_load_dwordx4 v[210:213], v[158:159], off offset:512
	global_load_dwordx4 v[198:201], v[166:167], off offset:576
	global_load_dwordx4 v[214:217], v[158:159], off offset:576
	v_lshl_add_u64 v[146:147], s[26:27], 0, v[146:147]
	v_lshl_add_u64 v[168:169], v[146:147], 0, v[144:145]
	s_mov_b64 s[6:7], 0
	s_waitcnt vmcnt(6)
	v_pk_fma_f32 v[146:147], v[26:27], v[204:205], v[188:189]
	v_pk_fma_f32 v[144:145], v[24:25], v[202:203], v[186:187]
	global_store_dwordx4 v[168:169], v[144:147], off
	s_waitcnt vmcnt(5)
	v_pk_fma_f32 v[192:193], v[18:19], v[208:209], v[192:193]
	v_pk_fma_f32 v[190:191], v[16:17], v[206:207], v[190:191]
	global_store_dwordx4 v[168:169], v[190:193], off offset:64
	s_waitcnt vmcnt(4)
	v_pk_fma_f32 v[196:197], v[6:7], v[212:213], v[196:197]
	v_pk_fma_f32 v[194:195], v[4:5], v[210:211], v[194:195]
	global_store_dwordx4 v[168:169], v[194:197], off offset:512
	s_waitcnt vmcnt(3)
	v_pk_fma_f32 v[200:201], v[2:3], v[216:217], v[200:201]
	v_pk_fma_f32 v[198:199], v[0:1], v[214:215], v[198:199]
	global_store_dwordx4 v[168:169], v[198:201], off offset:576
